# P0 XN stores plain instead of sc1
# speedup vs baseline: 1.0046x; 1.0046x over previous
.LBB0_97:
	s_waitcnt vmcnt(3)
	v_pk_mul_f32 v[90:91], v[78:79], v[78:79]
	v_pk_mul_f32 v[92:93], v[76:77], v[76:77]
	s_lshl_b64 s[20:21], s[20:21], 11
	v_pk_mov_b32 v[94:95], v[92:93], v[90:91] op_sel:[1,0]
	v_mov_b32_e32 v93, v91
	v_pk_add_f32 v[90:91], v[94:95], v[92:93]
	s_waitcnt vmcnt(2)
	v_pk_mul_f32 v[92:93], v[74:75], v[74:75]
	v_pk_mul_f32 v[94:95], v[72:73], v[72:73]
	v_pk_add_f32 v[90:91], v[90:91], v[90:91] op_sel:[0,1] op_sel_hi:[1,0]
	v_pk_mov_b32 v[96:97], v[94:95], v[92:93] op_sel:[1,0]
	v_mov_b32_e32 v95, v93
	v_pk_add_f32 v[92:93], v[96:97], v[94:95]
	s_waitcnt vmcnt(0)
	v_mul_f32_e32 v91, v64, v64
	v_pk_add_f32 v[92:93], v[92:93], v[92:93] op_sel:[0,1] op_sel_hi:[1,0]
	v_mul_f32_e32 v94, v71, v71
	v_mul_f32_e32 v93, v65, v65
	v_pk_add_f32 v[90:91], v[90:91], v[92:93]
	v_mul_f32_e32 v92, v69, v69
	v_pk_fma_f32 v[92:93], v[68:69], v[68:69], v[92:93] op_sel_hi:[1,1,0]
	v_pk_fma_f32 v[94:95], v[70:71], v[70:71], v[94:95] op_sel_hi:[1,1,0]
	v_mul_f32_e32 v93, v66, v66
	v_mul_f32_e32 v95, v67, v67
	v_pk_add_f32 v[92:93], v[92:93], v[94:95]
	v_mul_f32_e32 v94, v53, v53
	v_pk_add_f32 v[90:91], v[90:91], v[92:93]
	v_mul_f32_e32 v92, v61, v61
	v_add_f32_e32 v90, v90, v91
	ds_bpermute_b32 v91, v82, v90
	v_mul_f32_e32 v93, v63, v63
	v_fmac_f32_e32 v92, v60, v60
	v_fmac_f32_e32 v93, v62, v62
	v_fmac_f32_e32 v94, v52, v52
	s_waitcnt lgkmcnt(0)
	v_add_f32_e32 v90, v90, v91
	ds_bpermute_b32 v91, v83, v90
	s_andn2_b64 vcc, exec, s[18:19]
	s_waitcnt lgkmcnt(0)
	v_add_f32_e32 v90, v90, v91
	ds_bpermute_b32 v91, v84, v90
	s_waitcnt lgkmcnt(0)
	v_add_f32_e32 v90, v90, v91
	ds_bpermute_b32 v91, v85, v90
	s_waitcnt lgkmcnt(0)
	v_add_f32_e32 v90, v90, v91
	ds_bpermute_b32 v91, v86, v90
	s_waitcnt lgkmcnt(0)
	v_add_f32_e32 v90, v90, v91
	ds_bpermute_b32 v91, v87, v90
	s_waitcnt lgkmcnt(0)
	v_add_f32_e32 v90, v90, v91
	v_fmamk_f32 v90, v90, 0x3a800000, v89
	v_rsq_f32_e32 v90, v90
	v_add_f32_e32 v91, v92, v93
	v_mul_f32_e32 v92, v55, v55
	v_fmac_f32_e32 v92, v54, v54
	v_add_f32_e32 v92, v94, v92
	v_pk_mul_f32 v[76:77], v[90:91], v[76:77] op_sel_hi:[0,1]
	v_pk_mul_f32 v[78:79], v[90:91], v[78:79] op_sel_hi:[0,1]
	v_add_f32_e32 v91, v91, v92
	v_mul_f32_e32 v92, v45, v45
	v_mul_f32_e32 v93, v47, v47
	v_fmac_f32_e32 v92, v44, v44
	v_fmac_f32_e32 v93, v46, v46
	v_add_f32_e32 v92, v92, v93
	v_add_f32_e32 v91, v91, v92
	v_mul_f32_e32 v92, v33, v33
	v_mul_f32_e32 v93, v35, v35
	v_fmac_f32_e32 v92, v32, v32
	v_fmac_f32_e32 v93, v34, v34
	v_add_f32_e32 v92, v92, v93
	v_add_f32_e32 v91, v91, v92
	v_pk_mul_f32 v[78:79], v[78:79], v[2:3]
	v_pk_mul_f32 v[76:77], v[76:77], v[0:1]
	v_pk_mul_f32 v[72:73], v[90:91], v[72:73] op_sel_hi:[0,1]
	v_pk_mul_f32 v[74:75], v[90:91], v[74:75] op_sel_hi:[0,1]
	v_cvt_pk_bf16_f32 v76, v76, v77
	v_cvt_pk_bf16_f32 v77, v78, v79
	v_lshl_add_u64 v[78:79], v[80:81], 0, s[20:21]
	v_pk_mul_f32 v[74:75], v[74:75], v[6:7]
	v_pk_mul_f32 v[72:73], v[72:73], v[4:5]
	global_store_dwordx2 v[78:79], v[76:77], off
	s_nop 1
	v_mul_f32_e32 v76, v57, v57
	v_cvt_pk_bf16_f32 v72, v72, v73
	v_cvt_pk_bf16_f32 v73, v74, v75
	v_lshl_add_u64 v[74:75], v[78:79], 0, s[0:1]
	v_mul_f32_e32 v77, v59, v59
	global_store_dwordx2 v[74:75], v[72:73], off
	s_nop 1
	v_mul_f32_e32 v73, v17, v17
	v_mul_f32_e32 v74, v19, v19
	v_fmac_f32_e32 v76, v56, v56
	v_fmac_f32_e32 v77, v58, v58
	v_fmac_f32_e32 v73, v16, v16
	v_fmac_f32_e32 v74, v18, v18
	v_add_f32_e32 v76, v76, v77
	v_mul_f32_e32 v77, v49, v49
	v_mul_f32_e32 v92, v51, v51
	v_add_f32_e32 v73, v73, v74
	v_mul_f32_e32 v74, v41, v41
	v_mul_f32_e32 v75, v43, v43
	v_fmac_f32_e32 v77, v48, v48
	v_fmac_f32_e32 v92, v50, v50
	v_fmac_f32_e32 v74, v40, v40
	v_fmac_f32_e32 v75, v42, v42
	v_add_f32_e32 v77, v77, v92
	v_add_f32_e32 v74, v74, v75
	v_add_f32_e32 v76, v76, v77
	v_mul_f32_e32 v77, v37, v37
	v_mul_f32_e32 v92, v39, v39
	v_add_f32_e32 v73, v73, v74
	v_mul_f32_e32 v74, v29, v29
	v_mul_f32_e32 v75, v31, v31
	v_fmac_f32_e32 v77, v36, v36
	v_fmac_f32_e32 v92, v38, v38
	v_fmac_f32_e32 v74, v28, v28
	v_fmac_f32_e32 v75, v30, v30
	v_add_f32_e32 v77, v77, v92
	v_add_f32_e32 v74, v74, v75
	v_add_f32_e32 v76, v76, v77
	v_mul_f32_e32 v77, v25, v25
	v_mul_f32_e32 v92, v27, v27
	v_add_f32_e32 v73, v73, v74
	v_mul_f32_e32 v74, v21, v21
	v_mul_f32_e32 v75, v23, v23
	v_fmac_f32_e32 v77, v24, v24
	v_fmac_f32_e32 v92, v26, v26
	v_fmac_f32_e32 v74, v20, v20
	v_fmac_f32_e32 v75, v22, v22
	v_add_f32_e32 v77, v77, v92
	v_add_f32_e32 v74, v74, v75
	v_add_f32_e32 v76, v76, v77
	v_add_f32_e32 v73, v73, v74
	ds_bpermute_b32 v77, v82, v91
	ds_bpermute_b32 v72, v82, v76
	ds_bpermute_b32 v74, v82, v73
	s_waitcnt lgkmcnt(2)
	v_add_f32_e32 v75, v91, v77
	s_waitcnt lgkmcnt(1)
	v_add_f32_e32 v72, v76, v72
	s_waitcnt lgkmcnt(0)
	v_add_f32_e32 v73, v73, v74
	ds_bpermute_b32 v77, v83, v75
	ds_bpermute_b32 v76, v83, v72
	ds_bpermute_b32 v74, v83, v73
	s_waitcnt lgkmcnt(2)
	v_add_f32_e32 v75, v75, v77
	s_waitcnt lgkmcnt(1)
	v_add_f32_e32 v72, v72, v76
	s_waitcnt lgkmcnt(0)
	v_add_f32_e32 v73, v73, v74
	ds_bpermute_b32 v77, v84, v75
	ds_bpermute_b32 v76, v84, v72
	ds_bpermute_b32 v74, v84, v73
	s_waitcnt lgkmcnt(2)
	v_add_f32_e32 v75, v75, v77
	s_waitcnt lgkmcnt(1)
	v_add_f32_e32 v72, v72, v76
	s_waitcnt lgkmcnt(0)
	v_add_f32_e32 v73, v73, v74
	ds_bpermute_b32 v77, v85, v75
	ds_bpermute_b32 v76, v85, v72
	ds_bpermute_b32 v74, v85, v73
	s_waitcnt lgkmcnt(2)
	v_add_f32_e32 v75, v75, v77
	s_waitcnt lgkmcnt(1)
	v_add_f32_e32 v72, v72, v76
	s_waitcnt lgkmcnt(0)
	v_add_f32_e32 v92, v73, v74
	ds_bpermute_b32 v77, v86, v75
	ds_bpermute_b32 v91, v86, v72
	ds_bpermute_b32 v93, v86, v92
	s_waitcnt lgkmcnt(2)
	v_add_f32_e32 v75, v75, v77
	s_waitcnt lgkmcnt(1)
	v_add_f32_e32 v73, v72, v91
	s_waitcnt lgkmcnt(0)
	v_add_f32_e32 v72, v92, v93
	v_pk_mul_f32 v[92:93], v[90:91], v[68:69] op_sel_hi:[0,1]
	v_pk_mul_f32 v[70:71], v[90:91], v[70:71] op_sel_hi:[0,1]
	ds_bpermute_b32 v76, v87, v75
	ds_bpermute_b32 v74, v87, v73
	ds_bpermute_b32 v68, v87, v72
	v_pk_mul_f32 v[70:71], v[70:71], v[10:11]
	v_pk_mul_f32 v[92:93], v[92:93], v[8:9]
	v_pk_mul_f32 v[64:65], v[90:91], v[64:65] op_sel_hi:[0,1]
	v_cvt_pk_bf16_f32 v92, v92, v93
	v_cvt_pk_bf16_f32 v93, v70, v71
	v_lshl_add_u64 v[70:71], v[78:79], 0, s[4:5]
	v_pk_mul_f32 v[66:67], v[90:91], v[66:67] op_sel_hi:[0,1]
	v_pk_mul_f32 v[64:65], v[64:65], v[12:13]
	global_store_dwordx2 v[70:71], v[92:93], off
	s_nop 1
	v_pk_mul_f32 v[66:67], v[66:67], v[14:15]
	v_lshl_add_u64 v[70:71], v[78:79], 0, s[6:7]
	v_cvt_pk_bf16_f32 v64, v64, v65
	v_cvt_pk_bf16_f32 v65, v66, v67
	s_nop 0
	global_store_dwordx2 v[70:71], v[64:65], off
	s_nop 1
	s_cbranch_vccz .LBB0_100
	s_andn2_b64 vcc, exec, s[16:17]
	s_cbranch_vccz .LBB0_101

.LBB0_100:
	s_waitcnt lgkmcnt(2)
	v_add_f32_e32 v64, v75, v76
	v_fmamk_f32 v64, v64, 0x3a800000, v89
	v_rsq_f32_e32 v64, v64
	s_ashr_i32 s13, s12, 31
	s_lshl_b64 s[12:13], s[12:13], 11
	v_lshl_add_u64 v[66:67], v[80:81], 0, s[12:13]
	v_pk_mul_f32 v[60:61], v[64:65], v[60:61] op_sel_hi:[0,1]
	v_pk_mul_f32 v[62:63], v[64:65], v[62:63] op_sel_hi:[0,1]
	v_pk_mul_f32 v[60:61], v[60:61], v[0:1]
	v_pk_mul_f32 v[52:53], v[64:65], v[52:53] op_sel_hi:[0,1]
	v_pk_mul_f32 v[44:45], v[64:65], v[44:45] op_sel_hi:[0,1]
	v_pk_mul_f32 v[62:63], v[62:63], v[2:3]
	v_cvt_pk_bf16_f32 v60, v60, v61
	v_pk_mul_f32 v[54:55], v[64:65], v[54:55] op_sel_hi:[0,1]
	v_cvt_pk_bf16_f32 v61, v62, v63
	v_pk_mul_f32 v[52:53], v[52:53], v[4:5]
	v_pk_mul_f32 v[46:47], v[64:65], v[46:47] op_sel_hi:[0,1]
	v_pk_mul_f32 v[44:45], v[44:45], v[8:9]
	v_pk_mul_f32 v[32:33], v[64:65], v[32:33] op_sel_hi:[0,1]
	global_store_dwordx2 v[66:67], v[60:61], off
	s_nop 1
	v_pk_mul_f32 v[54:55], v[54:55], v[6:7]
	v_lshl_add_u64 v[60:61], v[66:67], 0, s[0:1]
	v_cvt_pk_bf16_f32 v52, v52, v53
	v_cvt_pk_bf16_f32 v53, v54, v55
	v_pk_mul_f32 v[46:47], v[46:47], v[10:11]
	global_store_dwordx2 v[60:61], v[52:53], off
	s_nop 1
	v_cvt_pk_bf16_f32 v44, v44, v45
	v_pk_mul_f32 v[34:35], v[64:65], v[34:35] op_sel_hi:[0,1]
	v_cvt_pk_bf16_f32 v45, v46, v47
	v_pk_mul_f32 v[32:33], v[32:33], v[12:13]
	v_lshl_add_u64 v[52:53], v[66:67], 0, s[4:5]
	global_store_dwordx2 v[52:53], v[44:45], off
	s_nop 1
	v_pk_mul_f32 v[34:35], v[34:35], v[14:15]
	v_lshl_add_u64 v[44:45], v[66:67], 0, s[6:7]
	v_cvt_pk_bf16_f32 v32, v32, v33
	v_cvt_pk_bf16_f32 v33, v34, v35
	s_nop 0
	global_store_dwordx2 v[44:45], v[32:33], off
	s_nop 1
	s_andn2_b64 vcc, exec, s[16:17]
	s_cbranch_vccnz .LBB0_99
.LBB0_101:
	s_waitcnt lgkmcnt(1)
	v_add_f32_e32 v32, v73, v74
	v_fmamk_f32 v32, v32, 0x3a800000, v89
	v_rsq_f32_e32 v32, v32
	s_ashr_i32 s11, s10, 31
	s_lshl_b64 s[10:11], s[10:11], 11
	v_lshl_add_u64 v[34:35], v[80:81], 0, s[10:11]
	v_pk_mul_f32 v[44:45], v[32:33], v[56:57] op_sel_hi:[0,1]
	v_pk_mul_f32 v[46:47], v[32:33], v[58:59] op_sel_hi:[0,1]
	v_pk_mul_f32 v[44:45], v[44:45], v[0:1]
	v_pk_mul_f32 v[46:47], v[46:47], v[2:3]
	v_cvt_pk_bf16_f32 v44, v44, v45
	v_pk_mul_f32 v[36:37], v[32:33], v[36:37] op_sel_hi:[0,1]
	v_cvt_pk_bf16_f32 v45, v46, v47
	v_pk_mul_f32 v[46:47], v[32:33], v[50:51] op_sel_hi:[0,1]
	global_store_dwordx2 v[34:35], v[44:45], off
	s_nop 1
	v_pk_mul_f32 v[44:45], v[32:33], v[48:49] op_sel_hi:[0,1]
	v_pk_mul_f32 v[44:45], v[44:45], v[4:5]
	v_pk_mul_f32 v[24:25], v[32:33], v[24:25] op_sel_hi:[0,1]
	v_pk_mul_f32 v[46:47], v[46:47], v[6:7]
	v_cvt_pk_bf16_f32 v44, v44, v45
	v_pk_mul_f32 v[38:39], v[32:33], v[38:39] op_sel_hi:[0,1]
	v_cvt_pk_bf16_f32 v45, v46, v47
	v_pk_mul_f32 v[36:37], v[36:37], v[8:9]
	v_pk_mul_f32 v[26:27], v[32:33], v[26:27] op_sel_hi:[0,1]
	v_pk_mul_f32 v[24:25], v[24:25], v[12:13]
	v_lshl_add_u64 v[48:49], v[34:35], 0, s[0:1]
	global_store_dwordx2 v[48:49], v[44:45], off
	s_nop 1
	v_pk_mul_f32 v[38:39], v[38:39], v[10:11]
	v_lshl_add_u64 v[44:45], v[34:35], 0, s[4:5]
	v_cvt_pk_bf16_f32 v36, v36, v37
	v_cvt_pk_bf16_f32 v37, v38, v39
	v_pk_mul_f32 v[26:27], v[26:27], v[14:15]
	global_store_dwordx2 v[44:45], v[36:37], off
	s_nop 1
	v_lshl_add_u64 v[32:33], v[34:35], 0, s[6:7]
	v_cvt_pk_bf16_f32 v24, v24, v25
	v_cvt_pk_bf16_f32 v25, v26, v27
	s_nop 0
	global_store_dwordx2 v[32:33], v[24:25], off
	s_nop 1
	s_andn2_b64 vcc, exec, s[14:15]
	s_cbranch_vccnz .LBB0_90
.LBB0_102:
	s_waitcnt lgkmcnt(0)
	v_add_f32_e32 v24, v72, v68
	v_fmamk_f32 v24, v24, 0x3a800000, v89
	v_rsq_f32_e32 v24, v24
	s_ashr_i32 s9, s8, 31
	s_lshl_b64 s[8:9], s[8:9], 11
	v_lshl_add_u64 v[26:27], v[80:81], 0, s[8:9]
	v_pk_mul_f32 v[16:17], v[24:25], v[16:17] op_sel_hi:[0,1]
	v_pk_mul_f32 v[18:19], v[24:25], v[18:19] op_sel_hi:[0,1]
	v_pk_mul_f32 v[16:17], v[16:17], v[0:1]
	v_pk_mul_f32 v[18:19], v[18:19], v[2:3]
	v_cvt_pk_bf16_f32 v16, v16, v17
	v_lshl_add_u64 v[32:33], v[26:27], 0, s[0:1]
	v_cvt_pk_bf16_f32 v17, v18, v19
	v_pk_mul_f32 v[18:19], v[24:25], v[42:43] op_sel_hi:[0,1]
	global_store_dwordx2 v[26:27], v[16:17], off
	s_nop 1
	v_pk_mul_f32 v[16:17], v[24:25], v[40:41] op_sel_hi:[0,1]
	v_pk_mul_f32 v[16:17], v[16:17], v[4:5]
	v_pk_mul_f32 v[18:19], v[18:19], v[6:7]
	v_cvt_pk_bf16_f32 v16, v16, v17
	s_nop 0
	v_cvt_pk_bf16_f32 v17, v18, v19
	v_pk_mul_f32 v[18:19], v[24:25], v[30:31] op_sel_hi:[0,1]
	global_store_dwordx2 v[32:33], v[16:17], off
	s_nop 1
	v_pk_mul_f32 v[16:17], v[24:25], v[28:29] op_sel_hi:[0,1]
	v_pk_mul_f32 v[16:17], v[16:17], v[8:9]
	v_pk_mul_f32 v[18:19], v[18:19], v[10:11]
	v_cvt_pk_bf16_f32 v16, v16, v17
	v_lshl_add_u64 v[28:29], v[26:27], 0, s[4:5]
	v_cvt_pk_bf16_f32 v17, v18, v19
	v_pk_mul_f32 v[18:19], v[24:25], v[22:23] op_sel_hi:[0,1]
	global_store_dwordx2 v[28:29], v[16:17], off
	s_nop 1
	v_pk_mul_f32 v[16:17], v[24:25], v[20:21] op_sel_hi:[0,1]
	v_pk_mul_f32 v[16:17], v[16:17], v[12:13]
	v_pk_mul_f32 v[18:19], v[18:19], v[14:15]
	v_lshl_add_u64 v[20:21], v[26:27], 0, s[6:7]
	v_cvt_pk_bf16_f32 v16, v16, v17
	v_cvt_pk_bf16_f32 v17, v18, v19
	s_nop 0
	global_store_dwordx2 v[20:21], v[16:17], off
	s_nop 1
	s_branch .LBB0_90
